# DF unit epilogue (wave 0): touches the next claimed DF unit's 256 Q lines so the next unit's Q loads find their misses in flight
# speedup vs baseline: 1.0048x; 1.0048x over previous
.LBB0_460:
	s_waitcnt lgkmcnt(0)
	s_barrier
	s_and_b64 vcc, exec, s[4:5]
	s_cbranch_vccnz .LBB0_299
	v_mov_b32_e32 v2, v217
	s_nop 1
	v_permlane32_swap_b32_e32 v217, v2
	v_add_f32_e32 v2, v217, v2
	v_div_scale_f32 v3, s[2:3], v2, v2, 1.0
	v_rcp_f32_e32 v4, v3
	s_waitcnt vmcnt(3)
	v_min_u32_e32 v253, 0xffff, v253
	v_or_b32_e32 v95, v95, v253
	v_lshlrev_b32_e32 v110, 16, v107
	v_and_b32_e32 v111, 0xffff0000, v107
	s_lshl_b64 s[2:3], s[6:7], 22
	v_fma_f32 v5, -v3, v4, 1.0
	v_fmac_f32_e32 v4, v5, v4
	v_div_scale_f32 v5, vcc, 1.0, v2, 1.0
	v_mul_f32_e32 v6, v5, v4
	v_fma_f32 v7, -v3, v6, v5
	v_fmac_f32_e32 v6, v7, v4
	v_fma_f32 v3, -v3, v6, v5
	v_div_fmas_f32 v3, v3, v4, v6
	v_div_fixup_f32 v94, v3, v2, 1.0
	ds_read2st64_b32 v[100:101], v0 offset1:1
	ds_read2st64_b32 v[98:99], v0 offset0:2 offset1:3
	ds_read2st64_b32 v[112:113], v0 offset0:4 offset1:5
	ds_read2st64_b32 v[108:109], v0 offset0:6 offset1:7
	ds_read2st64_b32 v[124:125], v0 offset0:8 offset1:9
	ds_read2st64_b32 v[128:129], v0 offset0:10 offset1:11
	ds_read2st64_b32 v[138:139], v0 offset0:12 offset1:13
	ds_read2st64_b32 v[186:187], v0 offset0:14 offset1:15
	ds_read2st64_b32 v[140:141], v0 offset0:16 offset1:17
	ds_read2st64_b32 v[136:137], v0 offset0:18 offset1:19
	ds_read2st64_b32 v[188:189], v0 offset0:20 offset1:21
	ds_read2st64_b32 v[194:195], v0 offset0:22 offset1:23
	ds_read2st64_b32 v[200:201], v0 offset0:24 offset1:25
	ds_read2st64_b32 v[192:193], v0 offset0:26 offset1:27
	ds_read2st64_b32 v[210:211], v0 offset0:28 offset1:29
	ds_read2st64_b32 v[202:203], v0 offset0:30 offset1:31
	ds_read2st64_b32 v[216:217], v0 offset0:32 offset1:33
	ds_read2st64_b32 v[212:213], v0 offset0:34 offset1:35
	ds_read2st64_b32 v[204:205], v0 offset0:36 offset1:37
	ds_read2st64_b32 v[208:209], v0 offset0:38 offset1:39
	ds_read2st64_b32 v[190:191], v0 offset0:40 offset1:41
	ds_read2st64_b32 v[198:199], v0 offset0:42 offset1:43
	ds_read2st64_b32 v[180:181], v0 offset0:44 offset1:45
	ds_read2st64_b32 v[182:183], v0 offset0:46 offset1:47
	ds_read2st64_b32 v[114:115], v0 offset0:56 offset1:57
	ds_read2st64_b32 v[116:117], v0 offset0:58 offset1:59
	ds_read2st64_b32 v[102:103], v0 offset0:60 offset1:61
	ds_read2st64_b32 v[2:3], v0 offset0:62 offset1:63
	ds_read2st64_b32 v[142:143], v0 offset0:48 offset1:49
	ds_read2st64_b32 v[144:145], v0 offset0:50 offset1:51
	ds_read2st64_b32 v[126:127], v0 offset0:52 offset1:53
	ds_read2st64_b32 v[130:131], v0 offset0:54 offset1:55
	s_waitcnt lgkmcnt(14)
	v_pk_fma_f32 v[100:101], v[64:65], v[94:95], v[100:101] op_sel_hi:[1,0,1] neg_lo:[0,0,1] neg_hi:[0,0,1]
	v_lshlrev_b32_e32 v64, 16, v106
	s_waitcnt lgkmcnt(4)
	v_pk_fma_f32 v[86:87], v[30:31], v[94:95], v[2:3] op_sel_hi:[1,0,1] neg_lo:[0,0,1] neg_hi:[0,0,1]
	v_and_b32_e32 v65, 0xffff0000, v106
	v_mul_f32_e32 v31, 0xbfb8aa3b, v64
	v_pk_fma_f32 v[98:99], v[66:67], v[94:95], v[98:99] op_sel_hi:[1,0,1] neg_lo:[0,0,1] neg_hi:[0,0,1]
	v_exp_f32_e32 v66, v31
	v_mul_f32_e32 v31, 0xbfb8aa3b, v65
	v_exp_f32_e32 v67, v31
	v_mul_f32_e32 v106, 0xbfb8aa3b, v110
	v_add_f32_e32 v66, 1.0, v66
	v_exp_f32_e32 v118, v106
	v_add_f32_e32 v67, 1.0, v67
	v_mul_f32_e32 v106, 0xbfb8aa3b, v111
	v_rcp_f32_e32 v66, v66
	v_rcp_f32_e32 v67, v67
	v_exp_f32_e32 v119, v106
	v_mul_f32_e32 v30, v101, v101
	v_pk_fma_f32 v[30:31], v[100:101], v[100:101], v[30:31] op_sel_hi:[1,1,0]
	v_pk_mul_f32 v[106:107], v[66:67], v[64:65]
	v_add_f32_e32 v64, 1.0, v118
	v_add_f32_e32 v65, 1.0, v119
	v_rcp_f32_e32 v64, v64
	v_rcp_f32_e32 v65, v65
	v_pk_fma_f32 v[30:31], v[98:99], v[98:99], v[30:31]
	v_mul_f32_e32 v66, v99, v99
	v_pk_add_f32 v[30:31], v[66:67], v[30:31] op_sel_hi:[0,1]
	v_lshlrev_b32_e32 v66, 16, v12
	v_and_b32_e32 v67, 0xffff0000, v12
	v_mul_f32_e32 v12, 0xbfb8aa3b, v66
	v_pk_mul_f32 v[110:111], v[64:65], v[110:111]
	v_exp_f32_e32 v12, v12
	v_mul_f32_e32 v65, 0xbfb8aa3b, v67
	v_exp_f32_e32 v65, v65
	v_pk_fma_f32 v[112:113], v[68:69], v[94:95], v[112:113] op_sel_hi:[1,0,1] neg_lo:[0,0,1] neg_hi:[0,0,1]
	v_add_f32_e32 v12, 1.0, v12
	v_pk_fma_f32 v[30:31], v[112:113], v[112:113], v[30:31]
	v_mul_f32_e32 v64, v113, v113
	v_pk_add_f32 v[30:31], v[64:65], v[30:31] op_sel_hi:[0,1]
	v_rcp_f32_e32 v64, v12
	v_add_f32_e32 v12, 1.0, v65
	v_rcp_f32_e32 v65, v12
	v_lshlrev_b32_e32 v12, 16, v13
	v_and_b32_e32 v13, 0xffff0000, v13
	v_mul_f32_e32 v68, 0xbfb8aa3b, v12
	v_mul_f32_e32 v69, 0xbfb8aa3b, v13
	v_exp_f32_e32 v68, v68
	v_exp_f32_e32 v69, v69
	v_pk_mul_f32 v[118:119], v[64:65], v[66:67]
	v_pk_fma_f32 v[108:109], v[70:71], v[94:95], v[108:109] op_sel_hi:[1,0,1] neg_lo:[0,0,1] neg_hi:[0,0,1]
	v_add_f32_e32 v64, 1.0, v68
	v_add_f32_e32 v65, 1.0, v69
	v_rcp_f32_e32 v64, v64
	v_rcp_f32_e32 v65, v65
	v_pk_fma_f32 v[30:31], v[108:109], v[108:109], v[30:31]
	v_mul_f32_e32 v66, v109, v109
	v_pk_add_f32 v[30:31], v[66:67], v[30:31] op_sel_hi:[0,1]
	v_pk_mul_f32 v[122:123], v[64:65], v[12:13]
	v_lshlrev_b32_e32 v64, 16, v10
	v_pk_fma_f32 v[72:73], v[72:73], v[94:95], v[124:125] op_sel_hi:[1,0,1] neg_lo:[0,0,1] neg_hi:[0,0,1]
	v_and_b32_e32 v65, 0xffff0000, v10
	v_mul_f32_e32 v10, 0xbfb8aa3b, v64
	v_pk_fma_f32 v[12:13], v[72:73], v[72:73], v[30:31]
	v_exp_f32_e32 v10, v10
	v_mul_f32_e32 v31, 0xbfb8aa3b, v65
	v_exp_f32_e32 v31, v31
	v_mul_f32_e32 v30, v73, v73
	v_add_f32_e32 v10, 1.0, v10
	v_pk_fma_f32 v[74:75], v[74:75], v[94:95], v[128:129] op_sel_hi:[1,0,1] neg_lo:[0,0,1] neg_hi:[0,0,1]
	v_pk_add_f32 v[12:13], v[30:31], v[12:13] op_sel_hi:[0,1]
	v_rcp_f32_e32 v30, v10
	v_add_f32_e32 v10, 1.0, v31
	v_rcp_f32_e32 v31, v10
	v_lshlrev_b32_e32 v10, 16, v11
	v_and_b32_e32 v11, 0xffff0000, v11
	v_mul_f32_e32 v66, 0xbfb8aa3b, v10
	v_mul_f32_e32 v67, 0xbfb8aa3b, v11
	v_exp_f32_e32 v66, v66
	v_exp_f32_e32 v67, v67
	v_pk_mul_f32 v[124:125], v[30:31], v[64:65]
	v_pk_fma_f32 v[12:13], v[74:75], v[74:75], v[12:13]
	v_add_f32_e32 v30, 1.0, v66
	v_add_f32_e32 v31, 1.0, v67
	v_rcp_f32_e32 v30, v30
	v_rcp_f32_e32 v31, v31
	v_mul_f32_e32 v64, v75, v75
	v_pk_add_f32 v[68:69], v[64:65], v[12:13] op_sel_hi:[0,1]
	v_pk_fma_f32 v[76:77], v[76:77], v[94:95], v[138:139] op_sel_hi:[1,0,1] neg_lo:[0,0,1] neg_hi:[0,0,1]
	v_lshlrev_b32_e32 v70, 16, v134
	v_and_b32_e32 v71, 0xffff0000, v134
	v_pk_mul_f32 v[128:129], v[30:31], v[10:11]
	v_pk_fma_f32 v[30:31], v[76:77], v[76:77], v[68:69]
	v_mul_f32_e32 v69, 0xbfb8aa3b, v70
	v_mul_f32_e32 v134, 0xbfb8aa3b, v71
	v_exp_f32_e32 v69, v69
	v_exp_f32_e32 v134, v134
	v_mul_f32_e32 v68, v77, v77
	v_lshlrev_b32_e32 v138, 16, v135
	v_pk_add_f32 v[30:31], v[68:69], v[30:31] op_sel_hi:[0,1]
	v_add_f32_e32 v68, 1.0, v69
	v_add_f32_e32 v69, 1.0, v134
	v_and_b32_e32 v139, 0xffff0000, v135
	v_mul_f32_e32 v134, 0xbfb8aa3b, v138
	v_exp_f32_e32 v148, v134
	v_mul_f32_e32 v134, 0xbfb8aa3b, v139
	v_rcp_f32_e32 v68, v68
	v_rcp_f32_e32 v69, v69
	v_exp_f32_e32 v149, v134
	v_pk_fma_f32 v[136:137], v[50:51], v[94:95], v[136:137] op_sel_hi:[1,0,1] neg_lo:[0,0,1] neg_hi:[0,0,1]
	v_lshlrev_b32_e32 v50, 16, v184
	v_pk_mul_f32 v[134:135], v[68:69], v[70:71]
	v_add_f32_e32 v68, 1.0, v148
	v_add_f32_e32 v69, 1.0, v149
	v_rcp_f32_e32 v68, v68
	v_rcp_f32_e32 v69, v69
	v_and_b32_e32 v51, 0xffff0000, v184
	v_pk_fma_f32 v[140:141], v[48:49], v[94:95], v[140:141] op_sel_hi:[1,0,1] neg_lo:[0,0,1] neg_hi:[0,0,1]
	v_mul_f32_e32 v49, 0xbfb8aa3b, v50
	v_pk_mul_f32 v[138:139], v[68:69], v[138:139]
	v_mul_f32_e32 v68, 0xbfb8aa3b, v51
	v_pk_fma_f32 v[78:79], v[78:79], v[94:95], v[186:187] op_sel_hi:[1,0,1] neg_lo:[0,0,1] neg_hi:[0,0,1]
	v_exp_f32_e32 v49, v49
	v_exp_f32_e32 v68, v68
	v_pk_fma_f32 v[30:31], v[78:79], v[78:79], v[30:31]
	v_mul_f32_e32 v70, v79, v79
	v_pk_add_f32 v[30:31], v[70:71], v[30:31] op_sel_hi:[0,1]
	v_pk_fma_f32 v[30:31], v[140:141], v[140:141], v[30:31]
	v_mul_f32_e32 v48, v141, v141
	v_pk_add_f32 v[30:31], v[48:49], v[30:31] op_sel_hi:[0,1]
	v_add_f32_e32 v48, 1.0, v49
	v_add_f32_e32 v49, 1.0, v68
	v_lshlrev_b32_e32 v0, 11, v179
	v_rcp_f32_e32 v48, v48
	v_rcp_f32_e32 v49, v49
	v_lshl_add_u64 v[2:3], s[56:57], 0, v[0:1]
	v_lshlrev_b32_e32 v68, 16, v185
	v_and_b32_e32 v69, 0xffff0000, v185
	v_pk_fma_f32 v[184:185], v[54:55], v[94:95], v[194:195] op_sel_hi:[1,0,1] neg_lo:[0,0,1] neg_hi:[0,0,1]
	v_lshlrev_b32_e32 v54, 16, v146
	v_and_b32_e32 v55, 0xffff0000, v146
	v_lshl_add_u64 v[2:3], v[2:3], 0, s[2:3]
	s_lshl_b32 s80, s16, 8
	v_pk_fma_f32 v[188:189], v[52:53], v[94:95], v[188:189] op_sel_hi:[1,0,1] neg_lo:[0,0,1] neg_hi:[0,0,1]
	v_mul_f32_e32 v53, 0xbfb8aa3b, v54
	v_mul_f32_e32 v146, 0xbfb8aa3b, v55
	v_lshl_add_u64 v[2:3], v[2:3], 0, s[80:81]
	v_ashrrev_i32_e32 v179, 31, v178
	v_exp_f32_e32 v53, v53
	v_exp_f32_e32 v146, v146
	v_lshl_add_u64 v[88:89], v[178:179], 1, v[2:3]
	v_lshl_add_u32 v0, v178, 2, 0
	v_pk_mul_f32 v[178:179], v[48:49], v[50:51]
	v_pk_fma_f32 v[30:31], v[136:137], v[136:137], v[30:31]
	v_mul_f32_e32 v50, v137, v137
	v_pk_add_f32 v[30:31], v[50:51], v[30:31] op_sel_hi:[0,1]
	v_pk_fma_f32 v[30:31], v[188:189], v[188:189], v[30:31]
	v_mul_f32_e32 v52, v189, v189
	v_lshlrev_b32_e32 v148, 16, v147
	v_pk_add_f32 v[30:31], v[52:53], v[30:31] op_sel_hi:[0,1]
	v_add_f32_e32 v52, 1.0, v53
	v_add_f32_e32 v53, 1.0, v146
	v_and_b32_e32 v149, 0xffff0000, v147
	v_mul_f32_e32 v146, 0xbfb8aa3b, v148
	v_exp_f32_e32 v150, v146
	v_mul_f32_e32 v146, 0xbfb8aa3b, v149
	v_rcp_f32_e32 v52, v52
	v_rcp_f32_e32 v53, v53
	v_exp_f32_e32 v151, v146
	v_pk_fma_f32 v[30:31], v[184:185], v[184:185], v[30:31]
	v_pk_fma_f32 v[200:201], v[56:57], v[94:95], v[200:201] op_sel_hi:[1,0,1] neg_lo:[0,0,1] neg_hi:[0,0,1]
	v_pk_mul_f32 v[146:147], v[52:53], v[54:55]
	v_add_f32_e32 v52, 1.0, v150
	v_add_f32_e32 v53, 1.0, v151
	v_rcp_f32_e32 v52, v52
	v_rcp_f32_e32 v53, v53
	v_mul_f32_e32 v54, v185, v185
	v_pk_add_f32 v[30:31], v[54:55], v[30:31] op_sel_hi:[0,1]
	v_lshlrev_b32_e32 v54, 16, v132
	v_and_b32_e32 v55, 0xffff0000, v132
	v_pk_mul_f32 v[194:195], v[52:53], v[148:149]
	v_mul_f32_e32 v53, 0xbfb8aa3b, v54
	v_mul_f32_e32 v56, 0xbfb8aa3b, v55
	v_exp_f32_e32 v53, v53
	v_exp_f32_e32 v56, v56
	v_pk_fma_f32 v[30:31], v[200:201], v[200:201], v[30:31]
	v_mul_f32_e32 v52, v201, v201
	v_pk_add_f32 v[30:31], v[52:53], v[30:31] op_sel_hi:[0,1]
	v_add_f32_e32 v52, 1.0, v53
	v_add_f32_e32 v53, 1.0, v56
	v_rcp_f32_e32 v52, v52
	v_rcp_f32_e32 v53, v53
	v_pk_fma_f32 v[202:203], v[62:63], v[94:95], v[202:203] op_sel_hi:[1,0,1] neg_lo:[0,0,1] neg_hi:[0,0,1]
	v_lshlrev_b32_e32 v62, 16, v120
	v_and_b32_e32 v63, 0xffff0000, v120
	v_pk_fma_f32 v[210:211], v[60:61], v[94:95], v[210:211] op_sel_hi:[1,0,1] neg_lo:[0,0,1] neg_hi:[0,0,1]
	v_mul_f32_e32 v61, 0xbfb8aa3b, v62
	v_mul_f32_e32 v120, 0xbfb8aa3b, v63
	v_pk_fma_f32 v[192:193], v[58:59], v[94:95], v[192:193] op_sel_hi:[1,0,1] neg_lo:[0,0,1] neg_hi:[0,0,1]
	v_exp_f32_e32 v61, v61
	v_exp_f32_e32 v120, v120
	v_lshlrev_b32_e32 v56, 16, v133
	v_and_b32_e32 v57, 0xffff0000, v133
	v_pk_mul_f32 v[132:133], v[52:53], v[54:55]
	v_pk_fma_f32 v[30:31], v[192:193], v[192:193], v[30:31]
	v_mul_f32_e32 v54, v193, v193
	v_pk_add_f32 v[30:31], v[54:55], v[30:31] op_sel_hi:[0,1]
	v_pk_fma_f32 v[30:31], v[210:211], v[210:211], v[30:31]
	v_mul_f32_e32 v60, v211, v211
	v_lshlrev_b32_e32 v148, 16, v121
	v_pk_add_f32 v[30:31], v[60:61], v[30:31] op_sel_hi:[0,1]
	v_add_f32_e32 v60, 1.0, v61
	v_add_f32_e32 v61, 1.0, v120
	v_and_b32_e32 v149, 0xffff0000, v121
	v_mul_f32_e32 v120, 0xbfb8aa3b, v148
	v_exp_f32_e32 v150, v120
	v_mul_f32_e32 v120, 0xbfb8aa3b, v149
	v_rcp_f32_e32 v60, v60
	v_rcp_f32_e32 v61, v61
	v_exp_f32_e32 v151, v120
	v_pk_fma_f32 v[212:213], v[34:35], v[94:95], v[212:213] op_sel_hi:[1,0,1] neg_lo:[0,0,1] neg_hi:[0,0,1]
	v_lshlrev_b32_e32 v34, 16, v104
	v_pk_mul_f32 v[120:121], v[60:61], v[62:63]
	v_add_f32_e32 v60, 1.0, v150
	v_add_f32_e32 v61, 1.0, v151
	v_rcp_f32_e32 v60, v60
	v_rcp_f32_e32 v61, v61
	v_and_b32_e32 v35, 0xffff0000, v104
	v_pk_fma_f32 v[216:217], v[32:33], v[94:95], v[216:217] op_sel_hi:[1,0,1] neg_lo:[0,0,1] neg_hi:[0,0,1]
	v_mul_f32_e32 v33, 0xbfb8aa3b, v34
	v_pk_mul_f32 v[214:215], v[60:61], v[148:149]
	v_mul_f32_e32 v60, 0xbfb8aa3b, v35
	v_exp_f32_e32 v33, v33
	v_exp_f32_e32 v60, v60
	v_pk_fma_f32 v[30:31], v[202:203], v[202:203], v[30:31]
	v_mul_f32_e32 v62, v203, v203
	v_pk_add_f32 v[30:31], v[62:63], v[30:31] op_sel_hi:[0,1]
	v_pk_fma_f32 v[30:31], v[216:217], v[216:217], v[30:31]
	v_mul_f32_e32 v32, v217, v217
	v_pk_add_f32 v[30:31], v[32:33], v[30:31] op_sel_hi:[0,1]
	v_add_f32_e32 v32, 1.0, v33
	v_add_f32_e32 v33, 1.0, v60
	v_rcp_f32_e32 v32, v32
	v_rcp_f32_e32 v33, v33
	v_pk_fma_f32 v[208:209], v[38:39], v[94:95], v[208:209] op_sel_hi:[1,0,1] neg_lo:[0,0,1] neg_hi:[0,0,1]
	v_lshlrev_b32_e32 v38, 16, v96
	v_and_b32_e32 v39, 0xffff0000, v96
	v_pk_fma_f32 v[204:205], v[36:37], v[94:95], v[204:205] op_sel_hi:[1,0,1] neg_lo:[0,0,1] neg_hi:[0,0,1]
	v_mul_f32_e32 v37, 0xbfb8aa3b, v38
	v_mul_f32_e32 v96, 0xbfb8aa3b, v39
	v_exp_f32_e32 v37, v37
	v_exp_f32_e32 v96, v96
	v_lshlrev_b32_e32 v60, 16, v105
	v_and_b32_e32 v61, 0xffff0000, v105
	v_pk_mul_f32 v[104:105], v[32:33], v[34:35]
	v_pk_fma_f32 v[30:31], v[212:213], v[212:213], v[30:31]
	v_mul_f32_e32 v34, v213, v213
	v_pk_add_f32 v[34:35], v[34:35], v[30:31] op_sel_hi:[0,1]
	v_pk_fma_f32 v[34:35], v[204:205], v[204:205], v[34:35]
	v_mul_f32_e32 v36, v205, v205
	v_lshlrev_b32_e32 v148, 16, v97
	v_pk_add_f32 v[34:35], v[36:37], v[34:35] op_sel_hi:[0,1]
	v_add_f32_e32 v36, 1.0, v37
	v_add_f32_e32 v37, 1.0, v96
	v_and_b32_e32 v149, 0xffff0000, v97
	v_mul_f32_e32 v96, 0xbfb8aa3b, v148
	v_exp_f32_e32 v150, v96
	v_mul_f32_e32 v96, 0xbfb8aa3b, v149
	v_rcp_f32_e32 v36, v36
	v_rcp_f32_e32 v37, v37
	v_exp_f32_e32 v151, v96
	v_pk_fma_f32 v[34:35], v[208:209], v[208:209], v[34:35]
	v_pk_fma_f32 v[190:191], v[40:41], v[94:95], v[190:191] op_sel_hi:[1,0,1] neg_lo:[0,0,1] neg_hi:[0,0,1]
	v_pk_mul_f32 v[96:97], v[36:37], v[38:39]
	v_add_f32_e32 v36, 1.0, v150
	v_add_f32_e32 v37, 1.0, v151
	v_rcp_f32_e32 v36, v36
	v_rcp_f32_e32 v37, v37
	v_mul_f32_e32 v38, v209, v209
	v_pk_add_f32 v[34:35], v[38:39], v[34:35] op_sel_hi:[0,1]
	v_lshlrev_b32_e32 v38, 16, v92
	v_and_b32_e32 v39, 0xffff0000, v92
	v_pk_mul_f32 v[220:221], v[36:37], v[148:149]
	v_mul_f32_e32 v37, 0xbfb8aa3b, v38
	v_mul_f32_e32 v40, 0xbfb8aa3b, v39
	v_exp_f32_e32 v37, v37
	v_exp_f32_e32 v40, v40
	v_pk_fma_f32 v[34:35], v[190:191], v[190:191], v[34:35]
	v_mul_f32_e32 v36, v191, v191
	v_pk_add_f32 v[34:35], v[36:37], v[34:35] op_sel_hi:[0,1]
	v_add_f32_e32 v36, 1.0, v37
	v_add_f32_e32 v37, 1.0, v40
	v_lshlrev_b32_e32 v40, 16, v93
	v_and_b32_e32 v41, 0xffff0000, v93
	v_pk_fma_f32 v[198:199], v[42:43], v[94:95], v[198:199] op_sel_hi:[1,0,1] neg_lo:[0,0,1] neg_hi:[0,0,1]
	v_rcp_f32_e32 v36, v36
	v_rcp_f32_e32 v37, v37
	v_mul_f32_e32 v42, 0xbfb8aa3b, v40
	v_mul_f32_e32 v43, 0xbfb8aa3b, v41
	v_exp_f32_e32 v42, v42
	v_exp_f32_e32 v43, v43
	v_lshlrev_b32_e32 v148, 16, v90
	v_and_b32_e32 v149, 0xffff0000, v90
	v_pk_fma_f32 v[180:181], v[44:45], v[94:95], v[180:181] op_sel_hi:[1,0,1] neg_lo:[0,0,1] neg_hi:[0,0,1]
	v_mul_f32_e32 v45, 0xbfb8aa3b, v148
	v_mul_f32_e32 v90, 0xbfb8aa3b, v149
	v_exp_f32_e32 v45, v45
	v_exp_f32_e32 v90, v90
	v_pk_mul_f32 v[92:93], v[36:37], v[38:39]
	v_pk_fma_f32 v[34:35], v[198:199], v[198:199], v[34:35]
	v_mul_f32_e32 v38, v199, v199
	v_add_f32_e32 v36, 1.0, v42
	v_add_f32_e32 v37, 1.0, v43
	v_pk_add_f32 v[42:43], v[38:39], v[34:35] op_sel_hi:[0,1]
	v_pk_fma_f32 v[42:43], v[180:181], v[180:181], v[42:43]
	v_mul_f32_e32 v44, v181, v181
	v_lshlrev_b32_e32 v150, 16, v91
	v_pk_add_f32 v[42:43], v[44:45], v[42:43] op_sel_hi:[0,1]
	v_add_f32_e32 v44, 1.0, v45
	v_add_f32_e32 v45, 1.0, v90
	v_and_b32_e32 v151, 0xffff0000, v91
	v_mul_f32_e32 v90, 0xbfb8aa3b, v150
	v_pk_fma_f32 v[46:47], v[46:47], v[94:95], v[182:183] op_sel_hi:[1,0,1] neg_lo:[0,0,1] neg_hi:[0,0,1]
	v_exp_f32_e32 v182, v90
	v_mul_f32_e32 v90, 0xbfb8aa3b, v151
	v_rcp_f32_e32 v44, v44
	v_rcp_f32_e32 v45, v45
	v_exp_f32_e32 v183, v90
	v_pk_fma_f32 v[42:43], v[46:47], v[46:47], v[42:43]
	s_waitcnt lgkmcnt(3)
	v_pk_fma_f32 v[142:143], v[16:17], v[94:95], v[142:143] op_sel_hi:[1,0,1] neg_lo:[0,0,1] neg_hi:[0,0,1]
	v_pk_mul_f32 v[90:91], v[44:45], v[148:149]
	v_add_f32_e32 v44, 1.0, v182
	v_add_f32_e32 v45, 1.0, v183
	v_rcp_f32_e32 v44, v44
	v_rcp_f32_e32 v45, v45
	v_mul_f32_e32 v148, v47, v47
	v_pk_add_f32 v[42:43], v[148:149], v[42:43] op_sel_hi:[0,1]
	v_pk_fma_f32 v[16:17], v[142:143], v[142:143], v[42:43]
	v_pk_mul_f32 v[182:183], v[44:45], v[150:151]
	v_lshlrev_b32_e32 v44, 16, v14
	v_and_b32_e32 v45, 0xffff0000, v14
	v_mul_f32_e32 v14, 0xbfb8aa3b, v44
	v_exp_f32_e32 v14, v14
	v_mul_f32_e32 v43, 0xbfb8aa3b, v45
	v_exp_f32_e32 v43, v43
	v_mul_f32_e32 v42, v143, v143
	v_add_f32_e32 v14, 1.0, v14
	s_waitcnt lgkmcnt(2)
	v_pk_fma_f32 v[18:19], v[18:19], v[94:95], v[144:145] op_sel_hi:[1,0,1] neg_lo:[0,0,1] neg_hi:[0,0,1]
	v_pk_add_f32 v[16:17], v[42:43], v[16:17] op_sel_hi:[0,1]
	v_rcp_f32_e32 v42, v14
	v_add_f32_e32 v14, 1.0, v43
	v_rcp_f32_e32 v43, v14
	v_lshlrev_b32_e32 v14, 16, v15
	v_and_b32_e32 v15, 0xffff0000, v15
	v_mul_f32_e32 v144, 0xbfb8aa3b, v14
	v_exp_f32_e32 v148, v144
	v_mul_f32_e32 v144, 0xbfb8aa3b, v15
	v_exp_f32_e32 v149, v144
	v_pk_mul_f32 v[144:145], v[42:43], v[44:45]
	v_pk_fma_f32 v[16:17], v[18:19], v[18:19], v[16:17]
	v_mul_f32_e32 v44, v19, v19
	v_add_f32_e32 v42, 1.0, v148
	v_add_f32_e32 v43, 1.0, v149
	v_pk_add_f32 v[148:149], v[44:45], v[16:17] op_sel_hi:[0,1]
	s_waitcnt lgkmcnt(1)
	v_pk_fma_f32 v[20:21], v[20:21], v[94:95], v[126:127] op_sel_hi:[1,0,1] neg_lo:[0,0,1] neg_hi:[0,0,1]
	s_waitcnt lgkmcnt(0)
	v_pk_fma_f32 v[22:23], v[22:23], v[94:95], v[130:131] op_sel_hi:[1,0,1] neg_lo:[0,0,1] neg_hi:[0,0,1]
	v_pk_fma_f32 v[126:127], v[20:21], v[20:21], v[148:149]
	s_waitcnt vmcnt(2)
	v_lshlrev_b32_e32 v148, 16, v84
	v_and_b32_e32 v149, 0xffff0000, v84
	v_mul_f32_e32 v84, 0xbfb8aa3b, v148
	v_exp_f32_e32 v84, v84
	v_mul_f32_e32 v131, 0xbfb8aa3b, v149
	v_exp_f32_e32 v131, v131
	v_mul_f32_e32 v130, v21, v21
	v_add_f32_e32 v84, 1.0, v84
	v_lshlrev_b32_e32 v150, 16, v85
	v_pk_add_f32 v[126:127], v[130:131], v[126:127] op_sel_hi:[0,1]
	v_rcp_f32_e32 v130, v84
	v_add_f32_e32 v84, 1.0, v131
	v_rcp_f32_e32 v131, v84
	v_and_b32_e32 v151, 0xffff0000, v85
	v_mul_f32_e32 v84, 0xbfb8aa3b, v150
	v_exp_f32_e32 v233, v84
	v_mul_f32_e32 v84, 0xbfb8aa3b, v151
	v_exp_f32_e32 v234, v84
	v_pk_mul_f32 v[84:85], v[130:131], v[148:149]
	v_add_f32_e32 v130, 1.0, v233
	v_rcp_f32_e32 v130, v130
	v_add_f32_e32 v131, 1.0, v234
	v_rcp_f32_e32 v131, v131
	v_pk_fma_f32 v[26:27], v[26:27], v[94:95], v[116:117] op_sel_hi:[1,0,1] neg_lo:[0,0,1] neg_hi:[0,0,1]
	s_waitcnt vmcnt(1)
	v_lshlrev_b32_e32 v116, 16, v82
	v_pk_fma_f32 v[126:127], v[22:23], v[22:23], v[126:127]
	v_mul_f32_e32 v148, v23, v23
	v_and_b32_e32 v117, 0xffff0000, v82
	v_mul_f32_e32 v82, 0xbfb8aa3b, v116
	v_pk_add_f32 v[148:149], v[148:149], v[126:127] op_sel_hi:[0,1]
	v_pk_mul_f32 v[126:127], v[130:131], v[150:151]
	v_exp_f32_e32 v82, v82
	v_mul_f32_e32 v130, 0xbfb8aa3b, v117
	v_exp_f32_e32 v130, v130
	v_pk_fma_f32 v[24:25], v[24:25], v[94:95], v[114:115] op_sel_hi:[1,0,1] neg_lo:[0,0,1] neg_hi:[0,0,1]
	v_add_f32_e32 v82, 1.0, v82
	v_rcp_f32_e32 v114, v82
	v_add_f32_e32 v82, 1.0, v130
	v_rcp_f32_e32 v115, v82
	v_pk_fma_f32 v[130:131], v[24:25], v[24:25], v[148:149]
	v_mul_f32_e32 v82, v25, v25
	v_pk_add_f32 v[130:131], v[82:83], v[130:131] op_sel_hi:[0,1]
	v_lshlrev_b32_e32 v82, 16, v83
	v_pk_mul_f32 v[234:235], v[114:115], v[116:117]
	v_mul_f32_e32 v116, 0xbfb8aa3b, v82
	v_exp_f32_e32 v117, v116
	v_pk_fma_f32 v[114:115], v[26:27], v[26:27], v[130:131]
	v_mul_f32_e32 v116, v27, v27
	v_pk_fma_f32 v[28:29], v[28:29], v[94:95], v[102:103] op_sel_hi:[1,0,1] neg_lo:[0,0,1] neg_hi:[0,0,1]
	v_pk_add_f32 v[114:115], v[116:117], v[114:115] op_sel_hi:[0,1]
	v_pk_fma_f32 v[102:103], v[28:29], v[28:29], v[114:115]
	v_mul_f32_e32 v94, v29, v29
	v_pk_add_f32 v[102:103], v[94:95], v[102:103] op_sel_hi:[0,1]
	v_pk_fma_f32 v[102:103], v[86:87], v[86:87], v[102:103]
	v_mul_f32_e32 v94, v87, v87
	v_pk_add_f32 v[102:103], v[94:95], v[102:103] op_sel_hi:[0,1]
	v_mov_b32_e32 v94, v102
	s_nop 1
	v_permlane32_swap_b32_e32 v102, v94
	v_add_f32_e32 v94, v102, v94
	v_mov_b32_e32 v102, 0x358637bd
	v_fmamk_f32 v94, v94, 0x3c000000, v102
	s_mov_b32 s2, 0xf800000
	v_mul_f32_e32 v102, 0x4f800000, v94
	v_cmp_gt_f32_e32 vcc, s2, v94
	v_add_f32_e32 v116, 1.0, v117
	v_mul_f32_e32 v70, 0xbfb8aa3b, v68
	v_cndmask_b32_e32 v94, v94, v102, vcc
	v_sqrt_f32_e32 v114, v94
	v_rcp_f32_e32 v102, v116
	v_mul_f32_e32 v71, 0xbfb8aa3b, v69
	v_mul_f32_e32 v58, 0xbfb8aa3b, v56
	v_add_u32_e32 v115, -1, v114
	v_fma_f32 v116, -v115, v114, v94
	v_cmp_ge_f32_e64 s[4:5], 0, v116
	v_add_u32_e32 v116, 1, v114
	v_mul_f32_e32 v59, 0xbfb8aa3b, v57
	v_cndmask_b32_e64 v115, v114, v115, s[4:5]
	v_fma_f32 v114, -v116, v114, v94
	v_mul_f32_e32 v62, 0xbfb8aa3b, v60
	v_mul_f32_e32 v63, 0xbfb8aa3b, v61
	v_cmp_lt_f32_e64 s[4:5], 0, v114
	v_exp_f32_e32 v70, v70
	v_exp_f32_e32 v71, v71
	v_exp_f32_e32 v58, v58
	v_exp_f32_e32 v59, v59
	v_exp_f32_e32 v62, v62
	v_exp_f32_e32 v63, v63
	v_and_b32_e32 v83, 0xffff0000, v83
	v_cndmask_b32_e64 v114, v115, v116, s[4:5]
	v_mul_f32_e32 v117, 0xbfb8aa3b, v83
	v_mul_f32_e32 v115, 0x37800000, v114
	v_exp_f32_e32 v117, v117
	v_cndmask_b32_e32 v114, v114, v115, vcc
	v_cmp_class_f32_e32 vcc, v94, v232
	s_mov_b32 s4, 0x3f4ccccd
	v_add_f32_e32 v48, 1.0, v70
	v_cndmask_b32_e32 v94, v114, v94, vcc
	v_add_f32_e32 v49, 1.0, v71
	v_add_f32_e32 v52, 1.0, v58
	v_add_f32_e32 v53, 1.0, v59
	v_add_f32_e32 v32, 1.0, v62
	v_add_f32_e32 v33, 1.0, v63
	v_div_scale_f32 v130, s[2:3], v94, v94, s4
	v_rcp_f32_e32 v48, v48
	v_rcp_f32_e32 v49, v49
	v_rcp_f32_e32 v52, v52
	v_rcp_f32_e32 v53, v53
	v_rcp_f32_e32 v32, v32
	v_rcp_f32_e32 v33, v33
	v_rcp_f32_e32 v36, v36
	v_rcp_f32_e32 v37, v37
	v_rcp_f32_e32 v42, v42
	v_rcp_f32_e32 v43, v43
	v_rcp_f32_e32 v131, v130
	v_add_f32_e32 v103, 1.0, v117
	v_rcp_f32_e32 v103, v103
	v_add_u32_e32 v0, 0x24800, v0
	ds_read_b128 v[6:9], v0
	ds_read_b128 v[2:5], v0 offset:32
	ds_read_b128 v[64:67], v0 offset:64
	ds_read_b128 v[10:13], v0 offset:96
	v_pk_mul_f32 v[186:187], v[48:49], v[68:69]
	ds_read_b128 v[68:71], v0 offset:128
	ds_read_b128 v[48:51], v0 offset:160
	v_pk_mul_f32 v[206:207], v[52:53], v[56:57]
	ds_read_b128 v[56:59], v0 offset:192
	ds_read_b128 v[52:55], v0 offset:224
	v_pk_mul_f32 v[218:219], v[32:33], v[60:61]
	ds_read_b128 v[60:63], v0 offset:256
	ds_read_b128 v[30:33], v0 offset:288
	v_pk_mul_f32 v[222:223], v[36:37], v[40:41]
	ds_read_b128 v[38:41], v0 offset:320
	ds_read_b128 v[34:37], v0 offset:352
	v_pk_mul_f32 v[224:225], v[42:43], v[14:15]
	ds_read_b128 v[42:45], v0 offset:384
	ds_read_b128 v[14:17], v0 offset:416
	ds_read_b128 v[114:117], v0 offset:448
	ds_read_b128 v[148:151], v0 offset:480
	v_fma_f32 v0, -v130, v131, 1.0
	v_fmac_f32_e32 v131, v0, v131
	v_div_scale_f32 v0, vcc, s4, v94, s4
	v_pk_mul_f32 v[82:83], v[102:103], v[82:83]
	v_mul_f32_e32 v102, v0, v131
	v_fma_f32 v103, -v130, v102, v0
	v_fmac_f32_e32 v102, v103, v131
	v_fma_f32 v0, -v130, v102, v0
	v_div_fmas_f32 v0, v0, v131, v102
	v_div_fixup_f32 v0, v0, v94, s4
	v_pk_mul_f32 v[100:101], v[100:101], v[0:1] op_sel_hi:[1,0]
	v_pk_mul_f32 v[98:99], v[98:99], v[0:1] op_sel_hi:[1,0]
	s_waitcnt lgkmcnt(14)
	v_pk_mul_f32 v[6:7], v[6:7], v[100:101]
	v_pk_mul_f32 v[8:9], v[8:9], v[98:99]
	v_pk_mul_f32 v[6:7], v[106:107], v[6:7]
	v_pk_mul_f32 v[8:9], v[110:111], v[8:9]
	v_cvt_pk_bf16_f32 v6, v6, v7
	v_cvt_pk_bf16_f32 v7, v8, v9
	global_store_dwordx2 v[88:89], v[6:7], off offset:1024
	v_pk_mul_f32 v[6:7], v[112:113], v[0:1] op_sel_hi:[1,0]
	s_nop 0
	v_pk_mul_f32 v[2:3], v[2:3], v[6:7]
	v_pk_mul_f32 v[6:7], v[108:109], v[0:1] op_sel_hi:[1,0]
	v_pk_mul_f32 v[2:3], v[118:119], v[2:3]
	v_pk_mul_f32 v[4:5], v[4:5], v[6:7]
	v_cvt_pk_bf16_f32 v2, v2, v3
	v_pk_mul_f32 v[4:5], v[122:123], v[4:5]
	s_waitcnt vmcnt(1)
	s_cmp_lg_u32 s63, 0
	s_cbranch_scc1 .Lqpf_end
	v_readfirstlane_b32 s2, v95
	s_lshr_b32 s3, s2, 16
	s_and_b32 s2, s2, 0xffff
	s_cmp_gt_u32 s3, 7
	s_cbranch_scc1 .Lqpf_end
	s_cmp_gt_u32 s2, 63
	s_cbranch_scc1 .Lqpf_end
	s_bfe_u32 s4, s2, 0x40001
	s_xor_b32 s4, s4, 15
	s_lshr_b32 s5, s2, 4
	s_and_b32 s5, s5, 2
	s_and_b32 s6, s2, 1
	s_or_b32 s5, s5, s6
	s_xor_b32 s5, s5, 2
	s_lshl_b32 s6, s3, 21
	s_lshl_b32 s5, s5, 19
	s_add_u32 s6, s6, s5
	s_lshl_b32 s4, s4, 15
	s_add_u32 s6, s6, s4
	s_add_u32 s6, s6, 0x4000000
	s_add_u32 s8, s78, s6
	s_addc_u32 s9, s79, 0
	v_lshlrev_b32_e32 v252, 7, v231
	global_load_dword v253, v252, s[8:9]
	v_add_u32_e32 v252, 0x2000, v252
	global_load_dword v253, v252, s[8:9]
	v_add_u32_e32 v252, 0x2000, v252
	global_load_dword v253, v252, s[8:9]
	v_add_u32_e32 v252, 0x2000, v252
	global_load_dword v253, v252, s[8:9]
.Lqpf_end:
	v_lshlrev_b32_e32 v6, 16, v80
	v_cvt_pk_bf16_f32 v3, v4, v5
	global_store_dwordx2 v[88:89], v[2:3], off offset:1040
	v_pk_mul_f32 v[2:3], v[72:73], v[0:1] op_sel_hi:[1,0]
	v_pk_mul_f32 v[4:5], v[74:75], v[0:1] op_sel_hi:[1,0]
	s_waitcnt lgkmcnt(13)
	v_pk_mul_f32 v[2:3], v[64:65], v[2:3]
	v_pk_mul_f32 v[4:5], v[66:67], v[4:5]
	v_pk_mul_f32 v[2:3], v[124:125], v[2:3]
	v_pk_mul_f32 v[4:5], v[128:129], v[4:5]
	v_cvt_pk_bf16_f32 v2, v2, v3
	v_cvt_pk_bf16_f32 v3, v4, v5
	global_store_dwordx2 v[88:89], v[2:3], off offset:1056
	v_pk_mul_f32 v[2:3], v[76:77], v[0:1] op_sel_hi:[1,0]
	v_pk_mul_f32 v[4:5], v[78:79], v[0:1] op_sel_hi:[1,0]
	s_waitcnt lgkmcnt(12)
	v_pk_mul_f32 v[2:3], v[2:3], v[10:11]
	v_pk_mul_f32 v[4:5], v[4:5], v[12:13]
	v_pk_mul_f32 v[2:3], v[134:135], v[2:3]
	v_pk_mul_f32 v[4:5], v[138:139], v[4:5]
	v_cvt_pk_bf16_f32 v2, v2, v3
	v_cvt_pk_bf16_f32 v3, v4, v5
	global_store_dwordx2 v[88:89], v[2:3], off offset:1072
	v_pk_mul_f32 v[2:3], v[140:141], v[0:1] op_sel_hi:[1,0]
	v_pk_mul_f32 v[4:5], v[136:137], v[0:1] op_sel_hi:[1,0]
	s_waitcnt lgkmcnt(11)
	v_pk_mul_f32 v[2:3], v[2:3], v[68:69]
	v_pk_mul_f32 v[4:5], v[4:5], v[70:71]
	v_pk_mul_f32 v[2:3], v[178:179], v[2:3]
	v_pk_mul_f32 v[4:5], v[186:187], v[4:5]
	v_cvt_pk_bf16_f32 v2, v2, v3
	v_cvt_pk_bf16_f32 v3, v4, v5
	global_store_dwordx2 v[88:89], v[2:3], off offset:1088
	v_pk_mul_f32 v[2:3], v[188:189], v[0:1] op_sel_hi:[1,0]
	v_pk_mul_f32 v[4:5], v[184:185], v[0:1] op_sel_hi:[1,0]
	s_waitcnt lgkmcnt(10)
	v_pk_mul_f32 v[2:3], v[2:3], v[48:49]
	v_pk_mul_f32 v[4:5], v[4:5], v[50:51]
	v_pk_mul_f32 v[2:3], v[146:147], v[2:3]
	v_pk_mul_f32 v[4:5], v[194:195], v[4:5]
	v_cvt_pk_bf16_f32 v2, v2, v3
	v_cvt_pk_bf16_f32 v3, v4, v5
	global_store_dwordx2 v[88:89], v[2:3], off offset:1104
	v_pk_mul_f32 v[2:3], v[200:201], v[0:1] op_sel_hi:[1,0]
	v_pk_mul_f32 v[4:5], v[192:193], v[0:1] op_sel_hi:[1,0]
	s_waitcnt lgkmcnt(9)
	v_pk_mul_f32 v[2:3], v[2:3], v[56:57]
	v_pk_mul_f32 v[4:5], v[4:5], v[58:59]
	v_pk_mul_f32 v[2:3], v[132:133], v[2:3]
	v_pk_mul_f32 v[4:5], v[206:207], v[4:5]
	v_cvt_pk_bf16_f32 v2, v2, v3
	v_cvt_pk_bf16_f32 v3, v4, v5
	global_store_dwordx2 v[88:89], v[2:3], off offset:1120
	v_pk_mul_f32 v[2:3], v[210:211], v[0:1] op_sel_hi:[1,0]
	v_pk_mul_f32 v[4:5], v[202:203], v[0:1] op_sel_hi:[1,0]
	s_waitcnt lgkmcnt(8)
	v_pk_mul_f32 v[2:3], v[2:3], v[52:53]
	v_pk_mul_f32 v[4:5], v[4:5], v[54:55]
	v_pk_mul_f32 v[2:3], v[120:121], v[2:3]
	v_pk_mul_f32 v[4:5], v[214:215], v[4:5]
	v_cvt_pk_bf16_f32 v2, v2, v3
	v_cvt_pk_bf16_f32 v3, v4, v5
	global_store_dwordx2 v[88:89], v[2:3], off offset:1136
	v_pk_mul_f32 v[2:3], v[216:217], v[0:1] op_sel_hi:[1,0]
	v_pk_mul_f32 v[4:5], v[212:213], v[0:1] op_sel_hi:[1,0]
	s_waitcnt lgkmcnt(7)
	v_pk_mul_f32 v[2:3], v[2:3], v[60:61]
	v_pk_mul_f32 v[4:5], v[4:5], v[62:63]
	v_pk_mul_f32 v[2:3], v[104:105], v[2:3]
	v_pk_mul_f32 v[4:5], v[218:219], v[4:5]
	v_cvt_pk_bf16_f32 v2, v2, v3
	v_cvt_pk_bf16_f32 v3, v4, v5
	global_store_dwordx2 v[88:89], v[2:3], off offset:1152
	v_pk_mul_f32 v[2:3], v[204:205], v[0:1] op_sel_hi:[1,0]
	v_pk_mul_f32 v[4:5], v[208:209], v[0:1] op_sel_hi:[1,0]
	s_waitcnt lgkmcnt(6)
	v_pk_mul_f32 v[2:3], v[2:3], v[30:31]
	v_pk_mul_f32 v[4:5], v[4:5], v[32:33]
	v_pk_mul_f32 v[2:3], v[96:97], v[2:3]
	v_pk_mul_f32 v[4:5], v[220:221], v[4:5]
	v_cvt_pk_bf16_f32 v2, v2, v3
	v_cvt_pk_bf16_f32 v3, v4, v5
	global_store_dwordx2 v[88:89], v[2:3], off offset:1168
	v_pk_mul_f32 v[2:3], v[190:191], v[0:1] op_sel_hi:[1,0]
	v_pk_mul_f32 v[4:5], v[198:199], v[0:1] op_sel_hi:[1,0]
	s_waitcnt lgkmcnt(5)
	v_pk_mul_f32 v[2:3], v[2:3], v[38:39]
	v_pk_mul_f32 v[4:5], v[4:5], v[40:41]
	v_pk_mul_f32 v[2:3], v[92:93], v[2:3]
	v_pk_mul_f32 v[4:5], v[222:223], v[4:5]
	v_cvt_pk_bf16_f32 v2, v2, v3
	v_cvt_pk_bf16_f32 v3, v4, v5
	global_store_dwordx2 v[88:89], v[2:3], off offset:1184
	v_pk_mul_f32 v[2:3], v[180:181], v[0:1] op_sel_hi:[1,0]
	v_pk_mul_f32 v[4:5], v[46:47], v[0:1] op_sel_hi:[1,0]
	s_waitcnt lgkmcnt(4)
	v_pk_mul_f32 v[2:3], v[2:3], v[34:35]
	v_pk_mul_f32 v[4:5], v[4:5], v[36:37]
	v_pk_mul_f32 v[2:3], v[90:91], v[2:3]
	v_pk_mul_f32 v[4:5], v[182:183], v[4:5]
	v_cvt_pk_bf16_f32 v2, v2, v3
	v_cvt_pk_bf16_f32 v3, v4, v5
	global_store_dwordx2 v[88:89], v[2:3], off offset:1200
	v_pk_mul_f32 v[2:3], v[142:143], v[0:1] op_sel_hi:[1,0]
	v_pk_mul_f32 v[4:5], v[18:19], v[0:1] op_sel_hi:[1,0]
	s_waitcnt lgkmcnt(3)
	v_pk_mul_f32 v[2:3], v[2:3], v[42:43]
	v_pk_mul_f32 v[4:5], v[4:5], v[44:45]
	v_pk_mul_f32 v[2:3], v[144:145], v[2:3]
	v_pk_mul_f32 v[4:5], v[224:225], v[4:5]
	v_cvt_pk_bf16_f32 v2, v2, v3
	v_cvt_pk_bf16_f32 v3, v4, v5
	global_store_dwordx2 v[88:89], v[2:3], off offset:1216
	v_pk_mul_f32 v[2:3], v[20:21], v[0:1] op_sel_hi:[1,0]
	v_pk_mul_f32 v[4:5], v[22:23], v[0:1] op_sel_hi:[1,0]
	s_waitcnt lgkmcnt(2)
	v_pk_mul_f32 v[2:3], v[2:3], v[14:15]
	v_pk_mul_f32 v[4:5], v[4:5], v[16:17]
	v_pk_mul_f32 v[2:3], v[84:85], v[2:3]
	v_pk_mul_f32 v[4:5], v[126:127], v[4:5]
	v_cvt_pk_bf16_f32 v2, v2, v3
	v_cvt_pk_bf16_f32 v3, v4, v5
	global_store_dwordx2 v[88:89], v[2:3], off offset:1232
	v_pk_mul_f32 v[2:3], v[24:25], v[0:1] op_sel_hi:[1,0]
	v_and_b32_e32 v7, 0xffff0000, v80
	s_waitcnt lgkmcnt(1)
	v_pk_mul_f32 v[2:3], v[2:3], v[114:115]
	v_pk_mul_f32 v[4:5], v[26:27], v[0:1] op_sel_hi:[1,0]
	v_pk_mul_f32 v[2:3], v[234:235], v[2:3]
	v_pk_mul_f32 v[4:5], v[4:5], v[116:117]
	v_cvt_pk_bf16_f32 v2, v2, v3
	v_mul_f32_e32 v3, 0xbfb8aa3b, v6
	v_exp_f32_e32 v8, v3
	v_mul_f32_e32 v3, 0xbfb8aa3b, v7
	v_exp_f32_e32 v9, v3
	v_pk_mul_f32 v[4:5], v[82:83], v[4:5]
	s_nop 0
	v_cvt_pk_bf16_f32 v3, v4, v5
	v_add_f32_e32 v4, 1.0, v8
	v_add_f32_e32 v5, 1.0, v9
	v_rcp_f32_e32 v4, v4
	v_rcp_f32_e32 v5, v5
	global_store_dwordx2 v[88:89], v[2:3], off offset:1248
	v_pk_mul_f32 v[2:3], v[28:29], v[0:1] op_sel_hi:[1,0]
	v_pk_mul_f32 v[4:5], v[4:5], v[6:7]
	v_lshlrev_b32_e32 v6, 16, v81
	v_and_b32_e32 v7, 0xffff0000, v81
	v_mul_f32_e32 v8, 0xbfb8aa3b, v6
	v_mul_f32_e32 v9, 0xbfb8aa3b, v7
	v_exp_f32_e32 v8, v8
	v_exp_f32_e32 v9, v9
	s_waitcnt lgkmcnt(0)
	v_pk_mul_f32 v[2:3], v[2:3], v[148:149]
	s_nop 0
	v_pk_mul_f32 v[2:3], v[4:5], v[2:3]
	v_add_f32_e32 v4, 1.0, v8
	v_add_f32_e32 v5, 1.0, v9
	v_rcp_f32_e32 v4, v4
	v_rcp_f32_e32 v5, v5
	v_pk_mul_f32 v[8:9], v[86:87], v[0:1] op_sel_hi:[1,0]
	v_cvt_pk_bf16_f32 v2, v2, v3
	v_pk_mul_f32 v[8:9], v[8:9], v[150:151]
	v_pk_mul_f32 v[4:5], v[4:5], v[6:7]
	s_nop 0
	v_pk_mul_f32 v[4:5], v[4:5], v[8:9]
	s_nop 0
	v_cvt_pk_bf16_f32 v3, v4, v5
	global_store_dwordx2 v[88:89], v[2:3], off offset:1264
	s_branch .LBB0_299
